# phase A (attn/kv items vs gather tail): co-resident workgroups take the two lists in opposite order (slot = blockIdx bit 8 instead of bit 0)
# speedup vs baseline: 1.0007x; 1.0007x over previous
; DEV int tid_() { int t = threadIdx.x; asm volatile("" : "+v"(t)); return t; }
; DEV int bid_() { int t = blockIdx.x; asm volatile("" : "+s"(t)); return t; }
; DEV int gdim_() { int t = gridDim.x; asm volatile("" : "+s"(t)); return t; }
; #define P (*launderP(lp))
; __device__ __forceinline__ void phase_peer_gather(PREF P, int slab, int tbeg, int tend) {
;   const int lane = tid_() & 63, wid = tid_() >> 6;
;   float* outs = P.out + (size_t)slab * TS * DM;
;   typedef const __attribute__((address_space(1))) unsigned char* gbytes_t;
;   gbytes_t U8 = (gbytes_t)P.Ub;
;   gbytes_t V8 = (gbytes_t)P.Vb;
;   for (int t = tbeg + bid_() * 4 + wid; t < tend; t += gdim_() * 4) {
;     const u16* hrow = P.hb + (size_t)t * 2048 + lane * 16;
; __global__ void __launch_bounds__(NTHR, 2) fwd_megakernel(Params Pk) {
;     ...
;       for (int part = 0; part < 2; ++part) {
;         if (part == cu_slot) {
;           for (int w = bid_(); w < 1024 + 3072; w += gdim_()) {
;             if (w < 1024) ret_kv_item(P, w, ST, smem);
;             else attn_item(P, w - 1024, Sshift, smem);
;           }
;         } else if (slab >= 1) {
;           phase_peer_gather(P, slab - 1, JSPLIT, TS);
.LBB0_149:
	v_readlane_b32 s1, v251, 0
	s_bfe_u32 s1, s1, 0x10008
	s_cmp_lg_u32 s0, s1
	s_mov_b64 s[0:1], -1
	s_cbranch_scc0 .LBB0_177
	s_andn2_b64 vcc, exec, s[4:5]
	s_cbranch_vccnz .LBB0_176
	v_mov_b32_e32 v53, 0x12400
	v_mov_b32_e32 v6, v188
	s_waitcnt lgkmcnt(0)
	v_mov_b32_e32 v0, v188
	v_readlane_b32 s0, v251, 0
	v_ashrrev_i32_e32 v7, 6, v0
	ds_read_b64 v[4:5], v53 offset:160
	ds_read2_b64 v[0:3], v53 offset0:26 offset1:27
	s_nop 0
	v_lshl_add_u32 v7, s0, 2, v7
	v_add_u32_e32 v48, 0x1800, v7
	s_movk_i32 s0, 0x2000
	v_cmp_gt_i32_e32 vcc, s0, v48
	s_and_saveexec_b64 s[0:1], vcc
	s_cbranch_execz .LBB0_175
	v_readlane_b32 s14, v251, 59
	v_readlane_b32 s15, v251, 60
	v_cmp_lt_i32_e32 vcc, v197, v198
	v_and_b32_e32 v52, 63, v6
	s_waitcnt lgkmcnt(0)
	v_lshl_add_u64 v[4:5], s[14:15], 2, v[4:5]
	s_brev_b32 s14, 63
	s_mov_b32 s15, -1
	v_lshl_add_u64 v[50:51], v[4:5], 0, s[14:15]
	v_cndmask_b32_e32 v4, v196, v197, vcc
	v_cmp_lt_i32_e32 vcc, v199, v198
	v_lshlrev_b32_e32 v138, 2, v4
	v_lshlrev_b32_e32 v54, 4, v52
	v_cndmask_b32_e32 v4, v196, v199, vcc
	v_cmp_lt_i32_e32 vcc, v200, v198
	v_lshlrev_b32_e32 v139, 2, v4
	v_mov_b32_e32 v55, v181
	v_cndmask_b32_e32 v4, v196, v200, vcc
	v_cmp_lt_i32_e32 vcc, v201, v198
	v_lshlrev_b32_e32 v140, 2, v4
	v_lshl_add_u64 v[56:57], v[0:1], 0, v[54:55]
	v_cndmask_b32_e32 v4, v196, v201, vcc
	v_cmp_lt_i32_e32 vcc, v202, v198
	v_lshlrev_b32_e32 v141, 2, v4
	v_lshl_add_u64 v[58:59], v[2:3], 0, v[54:55]
	v_cndmask_b32_e32 v4, v196, v202, vcc
	v_cmp_lt_i32_e32 vcc, v203, v198
	v_lshlrev_b32_e32 v142, 2, v4
	v_or_b32_e32 v0, 0x400, v54
	v_cndmask_b32_e32 v4, v196, v203, vcc
	v_lshlrev_b32_e32 v143, 2, v4
	v_or_b32_e32 v2, 0x404, v54
	v_or_b32_e32 v4, 0x408, v54
	v_or_b32_e32 v6, 0x40c, v54
	s_mov_b64 s[36:37], 0
	v_lshlrev_b32_e32 v180, 1, v54
	v_lshlrev_b32_e32 v60, 2, v0
	v_lshlrev_b32_e32 v62, 2, v2
	v_lshlrev_b32_e32 v64, 2, v4
	v_lshlrev_b32_e32 v66, 2, v6
	s_branch .LBB0_154
